# kept version plus P2 queue A: next ticket drawn by an atomic issued at the top of the current item (hides the dequeue round trip behind the item's first loads)
# baseline (speedup 1.0000x reference)
; #define LBAR() do { asm volatile("s_waitcnt lgkmcnt(0)" ::: "memory"); __builtin_amdgcn_s_barrier(); asm volatile("" ::: "memory"); } while (0)
; __device__ __forceinline__ float fast_exp(float x) { return __builtin_amdgcn_exp2f(x * LOG2E); }
; #define INP(k) (args_ptr()->in[k])
; __device__ __forceinline__ void gla_sample_item(Frame& F, int b, int h) {
;     ...
;     const size_t row0 = (size_t)MP + 8 * b;
;     { const int t = tid >> 6, k = tid & 63; const size_t r = row0 + t;
;       LA[tid] = fast_exp(bflo((unsigned)LOGA[r * 256 + h * 64 + k]));
;       LK[tid] = bflo((unsigned)KBp[r * 256 + h * 64 + k]); LQ[tid] = bflo((unsigned)QBp[r * 256 + h * 64 + k]);
; #pragma unroll
;       for (int i = 0; i < 2; ++i) { const int e = tid + 512 * i, tt = e >> 7, v = e & 127; LV[e] = bflo((unsigned)VBp[(row0 + tt) * 512 + h * 128 + v]); } }
;     const int v = tid & 127, kq = tid >> 7;
;     const float* sin_ = INP(I_SG) + ((size_t)(b * HB + h) * DKB + 16 * kq) * DVB + v;
;     float S[16];
; #pragma unroll
;     for (int i = 0; i < 16; ++i) S[i] = sin_[(size_t)i * DVB];
;     LBAR();
; #pragma unroll
;     for (int t = 0; t < 8; ++t) {
;         const float vt = LV[t * 128 + v]; float po = 0.f;
; #pragma unroll
;         for (int i = 0; i < 16; ++i) { const int k = 16 * kq + i; S[i] = LA[t * 64 + k] * S[i] + LK[t * 64 + k] * vt; po += LQ[t * 64 + k] * S[i]; }
; __device__ __forceinline__ void p2_run_a(Frame& F) {
;     int t = p2_fetch(F, CW_TICKET_A);
;     while (t < N_ATTS + N_GLAS) {
;         if (t < N_ATTS) { if (F.item_mask & 2) attn_sample_item(F, t >> 3, t & 7); }
;         else { const int i = t - N_ATTS; if (F.item_mask & 4) gla_sample_item(F, i >> 2, i & 3); }
;         t = p2_fetch(F, CW_TICKET_A);
.LBB0_782:
	s_and_saveexec_b64 s[98:99], s[10:11]
	s_cbranch_execz .Lapf_a
	v_mov_b32_e32 v230, 1
	global_atomic_add v230, v23, v230, s[58:59] offset:1280 sc0
.Lapf_a:
	s_or_b64 exec, exec, s[98:99]
	s_cmpk_gt_i32 s0, 0x3ff
	s_mov_b64 s[6:7], -1
	s_cbranch_scc0 .LBB0_786
	s_and_b64 vcc, exec, s[4:5]
	s_cbranch_vccnz .LBB0_785
	s_add_i32 s1, s0, 0xfffffc00
	s_lshr_b32 s8, s1, 2
	v_mov_b32_e32 v5, v0
	s_lshl_b32 s6, s8, 3
	v_ashrrev_i32_e32 v6, 6, v5
	s_add_i32 s14, s6, 0x10000
	v_ashrrev_i32_e32 v7, 31, v6
	s_and_b32 s1, s0, 3
	v_lshl_add_u64 v[2:3], v[6:7], 0, s[14:15]
	v_and_b32_e32 v4, 63, v5
	v_lshlrev_b64 v[2:3], 8, v[2:3]
	s_lshl_b32 s9, s1, 6
	s_lshl_b32 s1, s1, 8
	v_ashrrev_i32_e32 v14, 7, v5
	v_or3_b32 v2, v2, s9, v4
	v_and_b32_e32 v7, 0x7f, v5
	s_add_u32 s6, s49, s1
	v_ashrrev_i32_e32 v15, 31, v14
	v_lshlrev_b64 v[2:3], 1, v[2:3]
	s_addc_u32 s7, s50, 0
	v_lshlrev_b32_e32 v22, 1, v7
	v_lshl_add_u64 v[14:15], v[14:15], 0, s[14:15]
	v_lshl_add_u64 v[8:9], s[20:21], 0, v[2:3]
	v_lshl_add_u64 v[10:11], s[18:19], 0, v[2:3]
	v_lshl_add_u64 v[2:3], s[16:17], 0, v[2:3]
	v_lshl_add_u64 v[12:13], s[6:7], 0, v[22:23]
	v_lshlrev_b64 v[14:15], 10, v[14:15]
	v_lshl_add_u64 v[14:15], v[12:13], 0, v[14:15]
	global_load_ushort v8, v[8:9], off
	s_nop 0
	global_load_ushort v9, v[10:11], off
	s_nop 0
	global_load_ushort v10, v[2:3], off
	global_load_ushort v11, v[14:15], off
	v_add_u32_e32 v2, 0x200, v5
	v_ashrrev_i32_e32 v2, 7, v2
	v_ashrrev_i32_e32 v3, 31, v2
	v_lshl_add_u64 v[2:3], v[2:3], 0, s[14:15]
	v_lshlrev_b64 v[2:3], 10, v[2:3]
	v_lshl_add_u64 v[2:3], v[12:13], 0, v[2:3]
	global_load_ushort v2, v[2:3], off
	s_mov_b64 s[6:7], s[92:93]
	v_lshl_add_u32 v3, v5, 2, 0
	v_ashrrev_i32_e32 v12, 3, v5
	v_lshlrev_b32_e32 v22, 2, v7
	v_and_b32_e32 v5, 0x3fffff80, v5
	s_waitcnt vmcnt(4)
	v_lshlrev_b32_e32 v8, 16, v8
	v_mul_f32_e32 v8, 0x3fb8aa3b, v8
	v_exp_f32_e32 v8, v8
	s_waitcnt vmcnt(2)
	v_lshlrev_b32_e32 v10, 16, v10
	s_waitcnt vmcnt(1)
	v_lshlrev_b32_e32 v11, 16, v11
	v_lshlrev_b32_e32 v9, 16, v9
	s_waitcnt vmcnt(0)
	v_lshlrev_b32_e32 v2, 16, v2
	ds_write2st64_b32 v3, v10, v11 offset0:16 offset1:24
	ds_write_b32 v3, v2 offset:8192
	ds_write2st64_b32 v3, v8, v9 offset1:8
	v_and_b32_e32 v10, -16, v12
	v_mov_b64_e32 v[2:3], s[6:7]
	flat_load_dwordx2 v[8:9], v[2:3] offset:32
	s_lshl_b32 s6, s8, 8
	s_mov_b32 s7, s15
	v_ashrrev_i32_e32 v11, 31, v10
	s_or_b32 s6, s6, s9
	v_lshl_add_u64 v[2:3], v[10:11], 0, s[6:7]
	v_lshlrev_b64 v[2:3], 9, v[2:3]
	v_readfirstlane_b32 s6, v6
	v_lshl_or_b32 v6, v12, 2, 60
	v_lshl_add_u32 v7, v10, 2, 0
	v_add_u32_e32 v6, 0, v6
	s_lshl_b32 s7, s6, 11
	s_add_i32 s7, s7, 0
	s_waitcnt vmcnt(0) lgkmcnt(0)
	v_lshl_add_u64 v[8:9], v[8:9], 0, v[2:3]
	v_lshl_add_u64 v[8:9], v[8:9], 0, v[22:23]
	flat_load_dword v24, v[8:9]
	flat_load_dword v53, v[8:9] offset:512
	flat_load_dword v57, v[8:9] offset:1024
	flat_load_dword v61, v[8:9] offset:1536
	flat_load_dword v62, v[8:9] offset:2048
	flat_load_dword v63, v[8:9] offset:2560
	flat_load_dword v64, v[8:9] offset:3072
	flat_load_dword v65, v[8:9] offset:3584
	v_add_co_u32_e32 v8, vcc, s70, v8
	v_lshl_add_u64 v[2:3], s[22:23], 0, v[2:3]
	s_nop 0
	v_addc_co_u32_e32 v9, vcc, 0, v9, vcc
	flat_load_dword v66, v[8:9]
	flat_load_dword v67, v[8:9] offset:512
	flat_load_dword v68, v[8:9] offset:1024
	flat_load_dword v69, v[8:9] offset:1536
	flat_load_dword v70, v[8:9] offset:2048
	flat_load_dword v71, v[8:9] offset:2560
	flat_load_dword v72, v[8:9] offset:3072
	s_nop 0
	flat_load_dword v9, v[8:9] offset:3584
	v_add_u32_e32 v8, 0, v22
	s_waitcnt lgkmcnt(0)
	s_barrier
	ds_read_b32 v73, v8 offset:6144
	ds_read_b128 v[10:13], v7
	ds_read_b128 v[14:17], v7 offset:16
	ds_read_b128 v[18:21], v7 offset:32
	ds_read_b96 v[50:52], v7 offset:48
	ds_read_b128 v[26:29], v7 offset:2048
	ds_read_b128 v[30:33], v7 offset:2064
	ds_read_b128 v[34:37], v7 offset:2080
	ds_read_b128 v[38:41], v7 offset:4112
	ds_read_b128 v[42:45], v7 offset:4128
	ds_read_b128 v[46:49], v7 offset:4096
	ds_read_b96 v[54:56], v7 offset:2096
	ds_read_b96 v[58:60], v7 offset:4144
	ds_read_b32 v74, v6
	ds_read_b32 v75, v6 offset:2048
	ds_read_b32 v76, v6 offset:4096
	s_waitcnt lgkmcnt(0)
	v_mul_f32_e32 v77, v73, v26
	v_mul_f32_e32 v78, v73, v27
	v_mul_f32_e32 v79, v73, v28
	v_mul_f32_e32 v80, v73, v29
	v_mul_f32_e32 v81, v73, v30
	v_mul_f32_e32 v82, v73, v31
	v_mul_f32_e32 v83, v73, v32
	v_mul_f32_e32 v84, v73, v33
	v_mul_f32_e32 v85, v73, v34
	v_mul_f32_e32 v86, v73, v35
	v_mul_f32_e32 v87, v73, v36
	v_mul_f32_e32 v88, v73, v37
	v_mul_f32_e32 v89, v73, v54
	v_mul_f32_e32 v90, v73, v55
	v_mul_f32_e32 v91, v73, v56
	v_mul_f32_e32 v73, v73, v75
	v_lshl_add_u32 v5, v5, 2, v8
	v_lshl_add_u64 v[2:3], v[2:3], 0, v[22:23]
	v_lshlrev_b32_e32 v22, 2, v4
	s_waitcnt vmcnt(0)
	v_fmac_f32_e32 v77, v24, v10
	v_fmac_f32_e32 v78, v53, v11
	v_fma_f32 v10, v46, v77, 0
	v_fmac_f32_e32 v79, v57, v12
	v_fmac_f32_e32 v10, v47, v78
	v_fmac_f32_e32 v80, v61, v13
	v_fmac_f32_e32 v10, v48, v79
	v_fmac_f32_e32 v81, v62, v14
	v_fmac_f32_e32 v10, v49, v80
	v_fmac_f32_e32 v82, v63, v15
	v_fmac_f32_e32 v10, v38, v81
	v_fmac_f32_e32 v83, v64, v16
	v_fmac_f32_e32 v10, v39, v82
	v_fmac_f32_e32 v84, v65, v17
	v_fmac_f32_e32 v10, v40, v83
	v_fmac_f32_e32 v85, v66, v18
	v_fmac_f32_e32 v10, v41, v84
	v_fmac_f32_e32 v86, v67, v19
	v_fmac_f32_e32 v10, v42, v85
	v_fmac_f32_e32 v87, v68, v20
	v_fmac_f32_e32 v10, v43, v86
	v_fmac_f32_e32 v88, v69, v21
	v_fmac_f32_e32 v10, v44, v87
	v_fmac_f32_e32 v89, v70, v50
	v_fmac_f32_e32 v10, v45, v88
	v_fmac_f32_e32 v90, v71, v51
	v_fmac_f32_e32 v10, v58, v89
	v_fmac_f32_e32 v91, v72, v52
	v_fmac_f32_e32 v10, v59, v90
	v_fmac_f32_e32 v73, v9, v74
	v_fmac_f32_e32 v10, v60, v91
	v_fmac_f32_e32 v10, v76, v73
	ds_write_b32 v5, v10 offset:10240
	ds_read_b32 v9, v8 offset:6656
	ds_read_b128 v[10:13], v7 offset:256
	ds_read_b128 v[14:17], v7 offset:272
	ds_read_b128 v[18:21], v7 offset:288
	ds_read_b96 v[50:52], v7 offset:304
	ds_read_b128 v[26:29], v7 offset:2304
	ds_read_b128 v[30:33], v7 offset:2320
	ds_read_b128 v[34:37], v7 offset:2336
	ds_read_b128 v[38:41], v7 offset:4368
	ds_read_b128 v[42:45], v7 offset:4384
	ds_read_b128 v[46:49], v7 offset:4352
	ds_read_b96 v[54:56], v7 offset:2352
	ds_read_b96 v[58:60], v7 offset:4400
	ds_read_b32 v24, v6 offset:256
	ds_read_b32 v53, v6 offset:2304
	ds_read_b32 v57, v6 offset:4352
	s_waitcnt lgkmcnt(10)
; __device__ __forceinline__ void gla_sample_item(Frame& F, int b, int h) {
;     ...
;     for (int t = 0; t < 8; ++t) {
;         const float vt = LV[t * 128 + v]; float po = 0.f;
; #pragma unroll
;         for (int i = 0; i < 16; ++i) { const int k = 16 * kq + i; S[i] = LA[t * 64 + k] * S[i] + LK[t * 64 + k] * vt; po += LQ[t * 64 + k] * S[i]; }
;         LO[(t * 4 + kq) * 128 + v] = po;
	v_mul_f32_e32 v61, v9, v26
	v_mul_f32_e32 v62, v9, v27
	v_fmac_f32_e32 v61, v77, v10
	v_mul_f32_e32 v63, v9, v28
	v_fmac_f32_e32 v62, v78, v11
	s_waitcnt lgkmcnt(5)
	v_fma_f32 v10, v46, v61, 0
	v_mul_f32_e32 v64, v9, v29
	v_fmac_f32_e32 v63, v79, v12
	v_fmac_f32_e32 v10, v47, v62
	v_mul_f32_e32 v65, v9, v30
	v_fmac_f32_e32 v64, v80, v13
	v_fmac_f32_e32 v10, v48, v63
	v_mul_f32_e32 v66, v9, v31
	v_fmac_f32_e32 v65, v81, v14
	v_fmac_f32_e32 v10, v49, v64
	v_mul_f32_e32 v67, v9, v32
	v_fmac_f32_e32 v66, v82, v15
	v_fmac_f32_e32 v10, v38, v65
	v_mul_f32_e32 v68, v9, v33
	v_fmac_f32_e32 v67, v83, v16
	v_fmac_f32_e32 v10, v39, v66
	v_mul_f32_e32 v69, v9, v34
	v_fmac_f32_e32 v68, v84, v17
	v_fmac_f32_e32 v10, v40, v67
	v_mul_f32_e32 v70, v9, v35
	v_fmac_f32_e32 v69, v85, v18
	v_fmac_f32_e32 v10, v41, v68
	v_mul_f32_e32 v71, v9, v36
	v_fmac_f32_e32 v70, v86, v19
	v_fmac_f32_e32 v10, v42, v69
	v_mul_f32_e32 v72, v9, v37
	v_fmac_f32_e32 v71, v87, v20
	v_fmac_f32_e32 v10, v43, v70
	s_waitcnt lgkmcnt(4)
	v_mul_f32_e32 v74, v9, v54
	v_fmac_f32_e32 v72, v88, v21
	v_fmac_f32_e32 v10, v44, v71
	v_mul_f32_e32 v75, v9, v55
	v_fmac_f32_e32 v74, v89, v50
	v_fmac_f32_e32 v10, v45, v72
	v_mul_f32_e32 v76, v9, v56
	v_fmac_f32_e32 v75, v90, v51
	s_waitcnt lgkmcnt(3)
	v_fmac_f32_e32 v10, v58, v74
	s_waitcnt lgkmcnt(1)
	v_mul_f32_e32 v9, v9, v53
	v_fmac_f32_e32 v76, v91, v52
	v_fmac_f32_e32 v10, v59, v75
	v_fmac_f32_e32 v9, v73, v24
	v_fmac_f32_e32 v10, v60, v76
	s_waitcnt lgkmcnt(0)
	v_fmac_f32_e32 v10, v57, v9
	ds_write_b32 v5, v10 offset:12288
	ds_read_b32 v24, v8 offset:7168
	ds_read_b128 v[10:13], v7 offset:512
	ds_read_b128 v[14:17], v7 offset:528
	ds_read_b128 v[18:21], v7 offset:544
	ds_read_b96 v[50:52], v7 offset:560
	ds_read_b128 v[26:29], v7 offset:2560
	ds_read_b128 v[30:33], v7 offset:2576
	ds_read_b128 v[34:37], v7 offset:2592
	ds_read_b128 v[38:41], v7 offset:4624
	ds_read_b128 v[42:45], v7 offset:4640
	ds_read_b128 v[46:49], v7 offset:4608
	ds_read_b96 v[54:56], v7 offset:2608
	ds_read_b96 v[58:60], v7 offset:4656
	ds_read_b32 v53, v6 offset:512
	ds_read_b32 v57, v6 offset:2560
	ds_read_b32 v73, v6 offset:4608
	s_waitcnt lgkmcnt(10)
	v_mul_f32_e32 v77, v24, v26
	v_mul_f32_e32 v78, v24, v27
	v_mul_f32_e32 v79, v24, v28
	v_mul_f32_e32 v80, v24, v29
	s_waitcnt lgkmcnt(9)
	v_mul_f32_e32 v81, v24, v30
	v_mul_f32_e32 v82, v24, v31
	v_mul_f32_e32 v83, v24, v32
	v_mul_f32_e32 v84, v24, v33
	s_waitcnt lgkmcnt(8)
	v_mul_f32_e32 v85, v24, v34
	v_mul_f32_e32 v86, v24, v35
	v_mul_f32_e32 v87, v24, v36
	v_mul_f32_e32 v88, v24, v37
	s_waitcnt lgkmcnt(4)
	v_mul_f32_e32 v89, v24, v54
	v_mul_f32_e32 v90, v24, v55
	v_mul_f32_e32 v91, v24, v56
	s_waitcnt lgkmcnt(1)
	v_mul_f32_e32 v24, v24, v57
	v_fmac_f32_e32 v77, v61, v10
	v_fmac_f32_e32 v78, v62, v11
	v_fmac_f32_e32 v24, v9, v53
	v_fma_f32 v9, v46, v77, 0
	v_fmac_f32_e32 v79, v63, v12
	v_fmac_f32_e32 v9, v47, v78
	v_fmac_f32_e32 v80, v64, v13
	v_fmac_f32_e32 v9, v48, v79
	v_fmac_f32_e32 v81, v65, v14
	v_fmac_f32_e32 v9, v49, v80
	v_fmac_f32_e32 v82, v66, v15
	v_fmac_f32_e32 v9, v38, v81
	v_fmac_f32_e32 v83, v67, v16
	v_fmac_f32_e32 v9, v39, v82
	v_fmac_f32_e32 v84, v68, v17
	v_fmac_f32_e32 v9, v40, v83
	v_fmac_f32_e32 v85, v69, v18
	v_fmac_f32_e32 v9, v41, v84
	v_fmac_f32_e32 v86, v70, v19
	v_fmac_f32_e32 v9, v42, v85
	v_fmac_f32_e32 v87, v71, v20
	v_fmac_f32_e32 v9, v43, v86
	v_fmac_f32_e32 v88, v72, v21
	v_fmac_f32_e32 v9, v44, v87
	v_fmac_f32_e32 v89, v74, v50
	v_fmac_f32_e32 v9, v45, v88
	v_fmac_f32_e32 v90, v75, v51
	v_fmac_f32_e32 v9, v58, v89
	v_fmac_f32_e32 v91, v76, v52
	v_fmac_f32_e32 v9, v59, v90
	v_fmac_f32_e32 v9, v60, v91
	s_waitcnt lgkmcnt(0)
	v_fmac_f32_e32 v9, v73, v24
	ds_write_b32 v5, v9 offset:14336
	ds_read_b32 v9, v8 offset:7680
	ds_read_b128 v[10:13], v7 offset:768
	ds_read_b128 v[14:17], v7 offset:784
	ds_read_b128 v[18:21], v7 offset:800
	ds_read_b96 v[50:52], v7 offset:816
	ds_read_b128 v[26:29], v7 offset:2816
	ds_read_b128 v[30:33], v7 offset:2832
	ds_read_b128 v[34:37], v7 offset:2848
	ds_read_b128 v[38:41], v7 offset:4880
	ds_read_b128 v[42:45], v7 offset:4896
	ds_read_b128 v[46:49], v7 offset:4864
	ds_read_b96 v[54:56], v7 offset:2864
	ds_read_b96 v[58:60], v7 offset:4912
	s_waitcnt lgkmcnt(7)
	v_mul_f32_e32 v53, v9, v26
	v_mul_f32_e32 v57, v9, v27
	v_fmac_f32_e32 v53, v77, v10
	v_mul_f32_e32 v61, v9, v28
	v_fmac_f32_e32 v57, v78, v11
	s_waitcnt lgkmcnt(2)
	v_fma_f32 v10, v46, v53, 0
	v_mul_f32_e32 v62, v9, v29
	v_fmac_f32_e32 v61, v79, v12
	v_fmac_f32_e32 v10, v47, v57
	v_mul_f32_e32 v63, v9, v30
	v_fmac_f32_e32 v62, v80, v13
	v_fmac_f32_e32 v10, v48, v61
	v_mul_f32_e32 v64, v9, v31
	v_fmac_f32_e32 v63, v81, v14
	v_fmac_f32_e32 v10, v49, v62
	v_mul_f32_e32 v65, v9, v32
	v_fmac_f32_e32 v64, v82, v15
	v_fmac_f32_e32 v10, v38, v63
	v_mul_f32_e32 v66, v9, v33
	v_fmac_f32_e32 v65, v83, v16
	v_fmac_f32_e32 v10, v39, v64
	v_mul_f32_e32 v67, v9, v34
	v_fmac_f32_e32 v66, v84, v17
	v_fmac_f32_e32 v10, v40, v65
	v_mul_f32_e32 v68, v9, v35
	v_fmac_f32_e32 v67, v85, v18
	v_fmac_f32_e32 v10, v41, v66
	v_mul_f32_e32 v69, v9, v36
	v_fmac_f32_e32 v68, v86, v19
	v_fmac_f32_e32 v10, v42, v67
	v_mul_f32_e32 v70, v9, v37
	v_fmac_f32_e32 v69, v87, v20
	v_fmac_f32_e32 v10, v43, v68
	ds_read_b32 v11, v6 offset:768
	ds_read_b32 v12, v6 offset:2816
	ds_read_b32 v13, v6 offset:4864
	s_waitcnt lgkmcnt(4)
	v_mul_f32_e32 v54, v9, v54
	v_fmac_f32_e32 v70, v88, v21
	v_fmac_f32_e32 v10, v44, v69
	v_fmac_f32_e32 v54, v89, v50
	v_fmac_f32_e32 v10, v45, v70
	v_mul_f32_e32 v41, v9, v55
	s_waitcnt lgkmcnt(3)
	v_fmac_f32_e32 v10, v58, v54
	v_fmac_f32_e32 v41, v90, v51
	v_mul_f32_e32 v45, v9, v56
	v_fmac_f32_e32 v10, v59, v41
	v_fmac_f32_e32 v45, v91, v52
	s_waitcnt lgkmcnt(1)
; __device__ __forceinline__ void gla_sample_item(Frame& F, int b, int h) {
;     ...
;     for (int t = 0; t < 8; ++t) {
;         const float vt = LV[t * 128 + v]; float po = 0.f;
; #pragma unroll
;         for (int i = 0; i < 16; ++i) { const int k = 16 * kq + i; S[i] = LA[t * 64 + k] * S[i] + LK[t * 64 + k] * vt; po += LQ[t * 64 + k] * S[i]; }
;         LO[(t * 4 + kq) * 128 + v] = po;
	v_mul_f32_e32 v9, v9, v12
	v_fmac_f32_e32 v10, v60, v45
	v_fmac_f32_e32 v9, v24, v11
	s_waitcnt lgkmcnt(0)
	v_fmac_f32_e32 v10, v13, v9
	ds_write_b32 v5, v10 offset:16384
	ds_read_b96 v[38:40], v7 offset:1072
	ds_read_b128 v[10:13], v7 offset:3072
	ds_read_b32 v24, v8 offset:8192
	ds_read_b128 v[14:17], v7 offset:1024
	ds_read_b128 v[18:21], v7 offset:5120
	ds_read_b128 v[26:29], v7 offset:1040
	ds_read_b128 v[30:33], v7 offset:1056
	s_waitcnt lgkmcnt(4)
	v_mul_f32_e32 v46, v24, v10
	s_waitcnt lgkmcnt(3)
	v_fmac_f32_e32 v46, v53, v14
	v_mul_f32_e32 v48, v24, v11
	ds_read_b96 v[42:44], v7 offset:3120
	s_waitcnt lgkmcnt(3)
	v_fma_f32 v47, v18, v46, 0
	v_fmac_f32_e32 v48, v57, v15
	v_mul_f32_e32 v49, v24, v12
	v_mul_f32_e32 v50, v24, v13
	ds_read_b128 v[10:13], v7 offset:3088
	v_fmac_f32_e32 v47, v19, v48
	v_fmac_f32_e32 v49, v61, v16
	v_fmac_f32_e32 v47, v20, v49
	v_fmac_f32_e32 v50, v62, v17
	v_fmac_f32_e32 v47, v21, v50
	ds_read_b128 v[14:17], v7 offset:5136
	ds_read_b128 v[18:21], v7 offset:3104
	s_waitcnt lgkmcnt(2)
	v_mul_f32_e32 v51, v24, v10
	v_fmac_f32_e32 v51, v63, v26
	ds_read_b128 v[34:37], v7 offset:5152
	v_mul_f32_e32 v52, v24, v11
	s_waitcnt lgkmcnt(2)
	v_fmac_f32_e32 v47, v14, v51
	v_fmac_f32_e32 v52, v64, v27
	v_mul_f32_e32 v53, v24, v12
	v_fmac_f32_e32 v47, v15, v52
	v_fmac_f32_e32 v53, v65, v28
	v_mul_f32_e32 v55, v24, v13
	v_fmac_f32_e32 v47, v16, v53
	v_fmac_f32_e32 v55, v66, v29
	s_waitcnt lgkmcnt(1)
	v_mul_f32_e32 v56, v24, v18
	v_fmac_f32_e32 v47, v17, v55
	v_fmac_f32_e32 v56, v67, v30
	v_mul_f32_e32 v57, v24, v19
	ds_read_b96 v[10:12], v7 offset:5168
	s_waitcnt lgkmcnt(1)
	v_fmac_f32_e32 v47, v34, v56
	v_fmac_f32_e32 v57, v68, v31
	v_mul_f32_e32 v58, v24, v20
	v_fmac_f32_e32 v47, v35, v57
	v_fmac_f32_e32 v58, v69, v32
	v_mul_f32_e32 v59, v24, v21
	ds_read_b32 v13, v6 offset:1024
	ds_read_b32 v14, v6 offset:3072
	ds_read_b32 v15, v6 offset:5120
	v_fmac_f32_e32 v47, v36, v58
	v_fmac_f32_e32 v59, v70, v33
	v_mul_f32_e32 v60, v24, v42
	v_fmac_f32_e32 v47, v37, v59
	v_fmac_f32_e32 v60, v54, v38
	v_mul_f32_e32 v54, v24, v43
	s_waitcnt lgkmcnt(3)
	v_fmac_f32_e32 v47, v10, v60
	v_fmac_f32_e32 v54, v41, v39
	v_mul_f32_e32 v41, v24, v44
	v_fmac_f32_e32 v47, v11, v54
	v_fmac_f32_e32 v41, v45, v40
	s_waitcnt lgkmcnt(1)
	v_mul_f32_e32 v24, v24, v14
	v_fmac_f32_e32 v47, v12, v41
	v_fmac_f32_e32 v24, v9, v13
	s_waitcnt lgkmcnt(0)
	v_fmac_f32_e32 v47, v15, v24
	ds_write_b32 v5, v47 offset:18432
	ds_read_b96 v[38:40], v7 offset:1328
	ds_read_b128 v[10:13], v7 offset:3328
	ds_read_b32 v9, v8 offset:8704
	ds_read_b128 v[14:17], v7 offset:1280
	ds_read_b128 v[18:21], v7 offset:5376
	ds_read_b128 v[26:29], v7 offset:1296
	ds_read_b128 v[30:33], v7 offset:1312
	s_waitcnt lgkmcnt(4)
	v_mul_f32_e32 v45, v9, v10
	v_mul_f32_e32 v47, v9, v11
	s_waitcnt lgkmcnt(3)
	v_fmac_f32_e32 v45, v46, v14
	v_fmac_f32_e32 v47, v48, v15
	v_mul_f32_e32 v48, v9, v12
	ds_read_b96 v[42:44], v7 offset:3376
	s_waitcnt lgkmcnt(3)
	v_fma_f32 v46, v18, v45, 0
	v_fmac_f32_e32 v48, v49, v16
	v_mul_f32_e32 v49, v9, v13
	ds_read_b128 v[10:13], v7 offset:3344
	v_fmac_f32_e32 v46, v19, v47
	v_fmac_f32_e32 v46, v20, v48
	v_fmac_f32_e32 v49, v50, v17
	v_fmac_f32_e32 v46, v21, v49
	ds_read_b128 v[14:17], v7 offset:5392
	ds_read_b128 v[18:21], v7 offset:3360
	s_waitcnt lgkmcnt(2)
	v_mul_f32_e32 v50, v9, v10
	v_fmac_f32_e32 v50, v51, v26
	ds_read_b128 v[34:37], v7 offset:5408
	v_mul_f32_e32 v51, v9, v11
	s_waitcnt lgkmcnt(2)
	v_fmac_f32_e32 v46, v14, v50
	v_fmac_f32_e32 v51, v52, v27
	v_mul_f32_e32 v52, v9, v12
	v_fmac_f32_e32 v46, v15, v51
	v_fmac_f32_e32 v52, v53, v28
	v_mul_f32_e32 v53, v9, v13
	v_fmac_f32_e32 v46, v16, v52
	v_fmac_f32_e32 v53, v55, v29
	s_waitcnt lgkmcnt(1)
	v_mul_f32_e32 v55, v9, v18
	v_fmac_f32_e32 v46, v17, v53
	v_fmac_f32_e32 v55, v56, v30
	v_mul_f32_e32 v56, v9, v19
	ds_read_b96 v[10:12], v7 offset:5424
	s_waitcnt lgkmcnt(1)
	v_fmac_f32_e32 v46, v34, v55
	v_fmac_f32_e32 v56, v57, v31
	v_mul_f32_e32 v57, v9, v20
	v_fmac_f32_e32 v46, v35, v56
	v_fmac_f32_e32 v57, v58, v32
	v_mul_f32_e32 v58, v9, v21
	ds_read_b32 v13, v6 offset:1280
	ds_read_b32 v14, v6 offset:3328
	ds_read_b32 v15, v6 offset:5376
	v_fmac_f32_e32 v46, v36, v57
	v_fmac_f32_e32 v58, v59, v33
	v_mul_f32_e32 v59, v9, v42
	v_fmac_f32_e32 v46, v37, v58
	v_fmac_f32_e32 v59, v60, v38
	v_mul_f32_e32 v60, v9, v43
	s_waitcnt lgkmcnt(3)
	v_fmac_f32_e32 v46, v10, v59
	v_fmac_f32_e32 v60, v54, v39
	v_mul_f32_e32 v54, v9, v44
	v_fmac_f32_e32 v46, v11, v60
	v_fmac_f32_e32 v54, v41, v40
	s_waitcnt lgkmcnt(1)
	v_mul_f32_e32 v9, v9, v14
	v_fmac_f32_e32 v46, v12, v54
	v_fmac_f32_e32 v9, v24, v13
	s_waitcnt lgkmcnt(0)
	v_fmac_f32_e32 v46, v15, v9
	ds_write_b32 v5, v46 offset:20480
	ds_read_b96 v[38:40], v7 offset:1584
	ds_read_b128 v[10:13], v7 offset:3584
	ds_read_b32 v24, v8 offset:9216
	ds_read_b128 v[14:17], v7 offset:1536
	ds_read_b128 v[18:21], v7 offset:5632
	ds_read_b128 v[26:29], v7 offset:1552
	ds_read_b128 v[30:33], v7 offset:1568
	s_waitcnt lgkmcnt(4)
	v_mul_f32_e32 v41, v24, v10
	v_mul_f32_e32 v46, v24, v11
	s_waitcnt lgkmcnt(3)
	v_fmac_f32_e32 v41, v45, v14
	v_fmac_f32_e32 v46, v47, v15
	v_mul_f32_e32 v47, v24, v12
	ds_read_b96 v[42:44], v7 offset:3632
	s_waitcnt lgkmcnt(3)
	v_fma_f32 v45, v18, v41, 0
	v_fmac_f32_e32 v47, v48, v16
	v_mul_f32_e32 v48, v24, v13
	ds_read_b128 v[10:13], v7 offset:3600
	v_fmac_f32_e32 v45, v19, v46
	v_fmac_f32_e32 v45, v20, v47
	v_fmac_f32_e32 v48, v49, v17
	v_fmac_f32_e32 v45, v21, v48
	ds_read_b128 v[14:17], v7 offset:5648
	ds_read_b128 v[18:21], v7 offset:3616
	s_waitcnt lgkmcnt(2)
	v_mul_f32_e32 v49, v24, v10
	v_fmac_f32_e32 v49, v50, v26
	ds_read_b128 v[34:37], v7 offset:5664
	v_mul_f32_e32 v50, v24, v11
	s_waitcnt lgkmcnt(2)
; #define LAS __attribute__((address_space(3)))
; #define LBAR() do { asm volatile("s_waitcnt lgkmcnt(0)" ::: "memory"); __builtin_amdgcn_s_barrier(); asm volatile("" ::: "memory"); } while (0)
; __device__ __forceinline__ unsigned pk2(float lo, float hi) { typedef float f2 __attribute__((ext_vector_type(2))); typedef __bf16 b2 __attribute__((ext_vector_type(2))); f2 v = {lo, hi}; b2 b = __builtin_convertvector(v, b2); return __builtin_bit_cast(unsigned, b); }
; #define INP(k) (args_ptr()->in[k])
; __device__ __forceinline__ void gla_sample_item(Frame& F, int b, int h) {
;     ...
;         for (int i = 0; i < 16; ++i) { const int k = 16 * kq + i; S[i] = LA[t * 64 + k] * S[i] + LK[t * 64 + k] * vt; po += LQ[t * 64 + k] * S[i]; }
;         LO[(t * 4 + kq) * 128 + v] = po;
;     }
;     float* sout = F.out + OUT_SS + ((size_t)(b * HB + h) * DKB + 16 * kq) * DVB + v;
; #pragma unroll
;     for (int i = 0; i < 16; ++i) sout[(size_t)i * DVB] = S[i];
;     LBAR();
;     { const int t = w, v2 = 2 * lane;
;       float o0 = 0.f, o1 = 0.f;
; #pragma unroll
;       for (int q = 0; q < 4; ++q) { const f32x2 p = *(const LAS f32x2*)(LO + (t * 4 + q) * 128 + v2); o0 += p.x; o1 += p.y; }
;       const float ss = wave_sum(o0 * o0 + o1 * o1);
;       const float rn = __builtin_amdgcn_rsqf(ss * (1.0f / 128.0f) + EPS);
;       const unsigned gt = *(const unsigned*)(GBp + (row0 + t) * 512 + h * 128 + v2);
;       const f32x2 gw = *(const f32x2*)(INP(I_GNW) + v2);
;       *(unsigned*)(MIX + (row0 + t) * DM + DA + h * 128 + v2) = pk2(o0 * rn * gw.x * bflo(gt), o1 * rn * gw.y * bfhi(gt)); }
	v_fmac_f32_e32 v45, v14, v49
	v_fmac_f32_e32 v50, v51, v27
	v_mul_f32_e32 v51, v24, v12
	v_fmac_f32_e32 v45, v15, v50
	v_fmac_f32_e32 v51, v52, v28
	v_mul_f32_e32 v52, v24, v13
	v_fmac_f32_e32 v45, v16, v51
	v_fmac_f32_e32 v52, v53, v29
	s_waitcnt lgkmcnt(1)
	v_mul_f32_e32 v53, v24, v18
	v_fmac_f32_e32 v45, v17, v52
	v_fmac_f32_e32 v53, v55, v30
	v_mul_f32_e32 v55, v24, v19
	ds_read_b96 v[10:12], v7 offset:5680
	s_waitcnt lgkmcnt(1)
	v_fmac_f32_e32 v45, v34, v53
	v_fmac_f32_e32 v55, v56, v31
	v_mul_f32_e32 v56, v24, v20
	v_fmac_f32_e32 v45, v35, v55
	v_fmac_f32_e32 v56, v57, v32
	v_mul_f32_e32 v57, v24, v21
	ds_read_b32 v13, v6 offset:1536
	ds_read_b32 v14, v6 offset:3584
	ds_read_b32 v15, v6 offset:5632
	v_fmac_f32_e32 v45, v36, v56
	v_fmac_f32_e32 v57, v58, v33
	v_mul_f32_e32 v58, v24, v42
	v_fmac_f32_e32 v45, v37, v57
	v_fmac_f32_e32 v58, v59, v38
	v_mul_f32_e32 v59, v24, v43
	s_waitcnt lgkmcnt(3)
	v_fmac_f32_e32 v45, v10, v58
	v_fmac_f32_e32 v59, v60, v39
	v_mul_f32_e32 v60, v24, v44
	v_fmac_f32_e32 v45, v11, v59
	v_fmac_f32_e32 v60, v54, v40
	s_waitcnt lgkmcnt(1)
	v_mul_f32_e32 v24, v24, v14
	v_fmac_f32_e32 v45, v12, v60
	v_fmac_f32_e32 v24, v9, v13
	s_waitcnt lgkmcnt(0)
	v_fmac_f32_e32 v45, v15, v24
	ds_write_b32 v5, v45 offset:22528
	ds_read_b96 v[38:40], v7 offset:1840
	ds_read_b128 v[10:13], v7 offset:3840
	ds_read_b32 v45, v8 offset:9728
	ds_read_b128 v[14:17], v7 offset:1792
	ds_read_b128 v[18:21], v7 offset:5888
	ds_read_b128 v[26:29], v7 offset:1808
	ds_read_b128 v[30:33], v7 offset:1824
	s_waitcnt lgkmcnt(4)
	v_mul_f32_e32 v54, v45, v10
	s_waitcnt lgkmcnt(3)
	v_fmac_f32_e32 v54, v41, v14
	v_mul_f32_e32 v61, v45, v11
	ds_read_b96 v[42:44], v7 offset:3888
	ds_read_b128 v[8:11], v7 offset:3856
	s_waitcnt lgkmcnt(4)
	v_fma_f32 v41, v18, v54, 0
	v_fmac_f32_e32 v61, v46, v15
	v_mul_f32_e32 v46, v45, v12
	v_fmac_f32_e32 v41, v19, v61
	v_fmac_f32_e32 v46, v47, v16
	v_fmac_f32_e32 v41, v20, v46
	v_mul_f32_e32 v20, v45, v13
	v_fmac_f32_e32 v20, v48, v17
	ds_read_b128 v[12:15], v7 offset:5904
	ds_read_b128 v[16:19], v7 offset:3872
	v_fmac_f32_e32 v41, v21, v20
	s_waitcnt lgkmcnt(2)
	v_mul_f32_e32 v21, v45, v8
	v_fmac_f32_e32 v21, v49, v26
	s_waitcnt lgkmcnt(1)
	v_fmac_f32_e32 v41, v12, v21
	v_mul_f32_e32 v12, v45, v9
	ds_read_b128 v[34:37], v7 offset:5920
	v_fmac_f32_e32 v12, v50, v27
	v_fmac_f32_e32 v41, v13, v12
	v_mul_f32_e32 v13, v45, v10
	v_fmac_f32_e32 v13, v51, v28
	v_mul_f32_e32 v11, v45, v11
	v_fmac_f32_e32 v41, v14, v13
	v_fmac_f32_e32 v11, v52, v29
	s_waitcnt lgkmcnt(1)
	v_mul_f32_e32 v14, v45, v16
	v_fmac_f32_e32 v41, v15, v11
	v_fmac_f32_e32 v14, v53, v30
	v_mul_f32_e32 v15, v45, v17
	ds_read_b96 v[8:10], v7 offset:5936
	s_waitcnt lgkmcnt(1)
	v_fmac_f32_e32 v41, v34, v14
	v_fmac_f32_e32 v15, v55, v31
	v_mul_f32_e32 v16, v45, v18
	v_fmac_f32_e32 v41, v35, v15
	v_fmac_f32_e32 v16, v56, v32
	v_mul_f32_e32 v17, v45, v19
	v_fmac_f32_e32 v41, v36, v16
	v_fmac_f32_e32 v17, v57, v33
	v_mul_f32_e32 v18, v45, v42
	v_fmac_f32_e32 v41, v37, v17
	v_fmac_f32_e32 v18, v58, v38
	ds_read_b32 v7, v6 offset:1792
	ds_read_b32 v19, v6 offset:3840
	ds_read_b32 v6, v6 offset:5888
	s_waitcnt lgkmcnt(3)
	v_fmac_f32_e32 v41, v8, v18
	v_mul_f32_e32 v8, v45, v43
	v_fmac_f32_e32 v8, v59, v39
	v_fmac_f32_e32 v41, v9, v8
	v_mul_f32_e32 v9, v45, v44
	v_fmac_f32_e32 v9, v60, v40
	v_fmac_f32_e32 v41, v10, v9
	s_waitcnt lgkmcnt(1)
	v_mul_f32_e32 v10, v45, v19
	v_fmac_f32_e32 v10, v24, v7
	s_waitcnt lgkmcnt(0)
	v_fmac_f32_e32 v41, v6, v10
	ds_write_b32 v5, v41 offset:24576
	global_store_dword v[2:3], v54, off
	global_store_dword v[2:3], v61, off offset:512
	global_store_dword v[2:3], v46, off offset:1024
	global_store_dword v[2:3], v20, off offset:1536
	global_store_dword v[2:3], v21, off offset:2048
	global_store_dword v[2:3], v12, off offset:2560
	global_store_dword v[2:3], v13, off offset:3072
	global_store_dword v[2:3], v11, off offset:3584
	v_add_co_u32_e32 v2, vcc, s70, v2
	s_nop 1
	v_addc_co_u32_e32 v3, vcc, 0, v3, vcc
	global_store_dword v[2:3], v14, off
	global_store_dword v[2:3], v15, off offset:512
	global_store_dword v[2:3], v16, off offset:1024
	global_store_dword v[2:3], v17, off offset:1536
	global_store_dword v[2:3], v18, off offset:2048
	global_store_dword v[2:3], v8, off offset:2560
	global_store_dword v[2:3], v9, off offset:3072
	global_store_dword v[2:3], v10, off offset:3584
	v_lshlrev_b32_e32 v2, 3, v4
	v_add_u32_e32 v3, s7, v2
	s_ashr_i32 s7, s6, 31
	s_add_u32 s6, s6, s14
	s_addc_u32 s7, s7, 0
	s_lshl_b64 s[8:9], s[6:7], 10
	s_add_u32 s8, s51, s8
	s_addc_u32 s9, s52, s9
	s_add_u32 s8, s8, s1
	s_waitcnt lgkmcnt(0)
	s_barrier
	s_addc_u32 s9, s9, 0
	ds_read2st64_b64 v[6:9], v3 offset0:20 offset1:21
	ds_read2st64_b64 v[10:13], v3 offset0:22 offset1:23
	global_load_dword v14, v22, s[8:9]
	s_mov_b64 s[8:9], s[92:93]
	v_mov_b32_e32 v3, v23
	v_mov_b64_e32 v[4:5], s[8:9]
	flat_load_dwordx2 v[4:5], v[4:5] offset:88
	v_cmp_lt_i32_e32 vcc, v115, v114
	s_lshl_b64 s[6:7], s[6:7], 11
	s_add_u32 s6, s58, s6
	s_addc_u32 s7, s59, s7
	s_add_u32 s6, s6, s1
	s_addc_u32 s7, s7, 0
	s_waitcnt vmcnt(0) lgkmcnt(0)
	v_lshl_add_u64 v[2:3], v[4:5], 0, v[2:3]
	flat_load_dwordx2 v[2:3], v[2:3]
	v_cndmask_b32_e32 v4, v25, v115, vcc
	v_lshlrev_b32_e32 v15, 2, v4
	v_pk_add_f32 v[4:5], v[6:7], 0 op_sel_hi:[1,0]
	v_cmp_lt_i32_e32 vcc, v116, v114
	v_pk_add_f32 v[4:5], v[4:5], v[8:9]
	v_and_b32_e32 v9, 0xffff0000, v14
	v_pk_add_f32 v[4:5], v[4:5], v[10:11]
	v_cndmask_b32_e32 v8, v25, v116, vcc
	v_pk_add_f32 v[4:5], v[4:5], v[12:13]
	v_lshlrev_b32_e32 v8, 2, v8
	v_pk_mul_f32 v[6:7], v[4:5], v[4:5]
	v_cmp_lt_i32_e32 vcc, v117, v114
	v_add_f32_e32 v6, v6, v7
	ds_bpermute_b32 v7, v15, v6
	s_waitcnt lgkmcnt(0)
	v_add_f32_e32 v6, v6, v7
	ds_bpermute_b32 v7, v8, v6
	v_cndmask_b32_e32 v8, v25, v117, vcc
	v_lshlrev_b32_e32 v8, 2, v8
	v_cmp_lt_i32_e32 vcc, v118, v114
	s_waitcnt lgkmcnt(0)
	v_add_f32_e32 v6, v6, v7
	ds_bpermute_b32 v7, v8, v6
	v_cndmask_b32_e32 v8, v25, v118, vcc
	v_lshlrev_b32_e32 v8, 2, v8
	v_cmp_lt_i32_e32 vcc, v119, v114
	s_waitcnt lgkmcnt(0)
	v_add_f32_e32 v6, v6, v7
	ds_bpermute_b32 v7, v8, v6
	v_cndmask_b32_e32 v8, v25, v119, vcc
	v_lshlrev_b32_e32 v8, 2, v8
	v_cmp_lt_i32_e32 vcc, v120, v114
	s_waitcnt lgkmcnt(0)
	v_add_f32_e32 v6, v6, v7
	ds_bpermute_b32 v7, v8, v6
	v_cndmask_b32_e32 v8, v25, v120, vcc
	v_lshlrev_b32_e32 v8, 2, v8
	s_waitcnt lgkmcnt(0)
	v_add_f32_e32 v6, v6, v7
	ds_bpermute_b32 v7, v8, v6
	v_lshlrev_b32_e32 v8, 16, v14
	s_waitcnt lgkmcnt(0)
	v_add_f32_e32 v6, v6, v7
	v_fmamk_f32 v6, v6, 0x3c000000, v1
	v_rsq_f32_e32 v6, v6
	s_nop 0
	v_pk_mul_f32 v[4:5], v[4:5], v[6:7] op_sel_hi:[1,0]
	s_waitcnt vmcnt(0)
	v_pk_mul_f32 v[2:3], v[2:3], v[4:5]
	s_nop 0
	v_pk_mul_f32 v[2:3], v[2:3], v[8:9]
	s_nop 0
	v_cvt_pk_bf16_f32 v4, v2, v3
	v_lshl_add_u64 v[2:3], s[6:7], 0, v[22:23]
	v_add_co_u32_e32 v2, vcc, 0x38c00000, v2
	s_nop 1
	v_addc_co_u32_e32 v3, vcc, 0, v3, vcc
	global_store_dword v[2:3], v4, off offset:1024
	s_waitcnt lgkmcnt(0)
	s_barrier

; #define LBAR() do { asm volatile("s_waitcnt lgkmcnt(0)" ::: "memory"); __builtin_amdgcn_s_barrier(); asm volatile("" ::: "memory"); } while (0)
; __device__ __forceinline__ int p2_fetch(Frame& F, int cw) {
;     if (F.tid == 0) F.MISC[4] = __hip_atomic_fetch_add(F.ctl + cw, 1u, RLX_AGENT);
;     LBAR(); const int t = __builtin_amdgcn_readfirstlane((int)F.MISC[4]); LBAR(); return t;
; }
; __device__ __forceinline__ void p2_run_a(Frame& F) {
;     int t = p2_fetch(F, CW_TICKET_A);
;     while (t < N_ATTS + N_GLAS) {
;         if (t < N_ATTS) { if (F.item_mask & 2) attn_sample_item(F, t >> 3, t & 7); }
;         else { const int i = t - N_ATTS; if (F.item_mask & 4) gla_sample_item(F, i >> 2, i & 3); }
;         t = p2_fetch(F, CW_TICKET_A);
.LBB0_850:
	s_and_saveexec_b64 s[6:7], s[10:11]
	s_cbranch_execz .LBB0_781
	s_mov_b64 s[12:13], exec
	v_mbcnt_lo_u32_b32 v2, s12, 0
	v_mbcnt_hi_u32_b32 v2, s13, v2
	v_cmp_eq_u32_e32 vcc, 0, v2
	s_and_saveexec_b64 s[8:9], vcc
	s_cbranch_execz .LBB0_780
	s_bcnt1_i32_b64 s0, s[12:13]
	v_mov_b32_e32 v3, s0
	s_waitcnt vmcnt(0)
	v_mov_b32_e32 v3, v230
	s_branch .LBB0_780
